# windows 7/8/8 items per idle WG (L1 FFN1 window raised to 8) with de-serialised store ladder
# baseline (speedup 1.0000x reference)
; __global__ void __launch_bounds__(NTHREADS, 2) mega_fwd(Args args) {
;     ...
;         for (int it = bid; it < DEPTH * I_LAYER; it += G, nbuf ^= 1) {
;             const int itr = DEPTH * I_LAYER - 1 - it;
;             const int l = itr / I_LAYER; int r = itr - l * I_LAYER;
;             unsigned char* WL = P_WL(l);
;             const float* W; int K, N, mode = 0; bf16* WT; const float* rg = nullptr;
;             if (r < 3 * I_GU) { const int w = r / I_GU; r -= w * I_GU;
;                 if (w < 2) { W = args.in[2 + w] + (size_t)l * D * FF; K = D; N = FF; WT = (bf16*)(WL + OFF_WGU1); rg = args.in[1] + (size_t)l * D; mode = 1 + w; }
;                 else { W = args.in[4] + (size_t)l * FF * D; K = FF; N = D; WT = (bf16*)(WL + OFF_WD1); } }
;             else if ((r -= 3 * I_GU) < 3 * I_GU) { const int w = r / I_GU; r -= w * I_GU;
;                 if (w < 2) { W = args.in[13 + w] + (size_t)l * D * FF; K = D; N = FF; WT = (bf16*)(WL + OFF_WGU2); rg = args.in[12] + (size_t)l * D; mode = 1 + w; }
;                 else { W = args.in[15] + (size_t)l * FF * D; K = FF; N = D; WT = (bf16*)(WL + OFF_WD2); } }
;             else if ((r -= 3 * I_GU) < I_IN) { W = args.in[6] + (size_t)l * D * INW; K = D; N = INW; WT = (bf16*)(WL + OFF_WIN); rg = args.in[5] + (size_t)l * D; mode = 3; }
;             else { r -= I_IN; W = args.in[11] + (size_t)l * D * D; K = D; N = D; WT = (bf16*)(WL + OFF_WOUT); }
;             tr_item_cu(W, K, N, WT, rg, mode, lds + nbuf * TC_BUF, r, wave, lane);
;         }
.Ldc_setup:
	v_readlane_b32 s4, v255, 28
	v_readlane_b32 s0, v255, 62
	v_readlane_b32 s1, v255, 63
	v_readlane_b32 s12, v254, 0
	v_readlane_b32 s13, v254, 1
	v_mov_b32_e32 v2, v211
	s_cmp_lg_u32 s4, 0
	s_cselect_b32 s4, 2, 0
	s_and_b32 s5, s98, 3
	s_add_i32 s4, s4, s5
	s_lshr_b32 s5, s98, 2
	s_lshl_b32 s4, s4, 2
	s_or_b32 s4, s4, s5
	s_mov_b32 s99, 1
	s_mov_b32 s101, 0
	s_cmp_eq_u32 s4, 4
	s_cselect_b32 s99, 2400, s99
	s_cselect_b32 s101, 2495, s101
	s_cmp_eq_u32 s4, 5
	s_cselect_b32 s99, 2624, s99
	s_cselect_b32 s101, 3423, s101
	s_cmp_eq_u32 s4, 8
	s_cselect_b32 s99, 0, s99
	s_cselect_b32 s101, 127, s101
	s_cmp_eq_u32 s4, 9
	s_cselect_b32 s99, 1504, s99
	s_cselect_b32 s101, 2399, s101
	s_cmp_eq_u32 s4, 12
	s_cselect_b32 s99, 128, s99
	s_cselect_b32 s101, 383, s101
	s_cmp_eq_u32 s4, 13
	s_cselect_b32 s99, 736, s99
	s_cselect_b32 s101, 1503, s101
	s_cmp_eq_u32 s4, 16
	s_cselect_b32 s99, 384, s99
	s_cselect_b32 s101, 735, s101
	s_cmp_gt_i32 s99, s101
	s_cbranch_scc1 .Ldc_finish
	s_sub_i32 s5, s72, 0x80
	s_add_i32 s99, s99, s5
	s_cmp_gt_i32 s99, s101
	s_cbranch_scc1 .Ldc_nextpass
	s_movk_i32 s100, 0x80
	s_waitcnt lgkmcnt(0)
	s_nop 4
	s_branch .Ldc_pre
